# v41 plus loop-head LDS reads hoisted above the scalar next-tile address arithmetic in the GU and Down steady loops
# speedup vs baseline: 1.0008x; 1.0008x over previous
.LBB0_532:
	ds_read_b128 v[138:141], v240
	ds_read_b128 v[142:145], v240 offset:1024
	ds_read_b128 v[148:151], v240 offset:2048
	ds_read_b128 v[152:155], v240 offset:3072
	ds_read_b128 v[156:159], v240 offset:16384
	ds_read_b128 v[160:163], v240 offset:17408
	ds_read_b128 v[164:167], v240 offset:18432
	ds_read_b128 v[168:171], v240 offset:19456
	ds_read_b128 v[172:175], v146
	ds_read_b128 v[176:179], v146 offset:1024
	ds_read_b128 v[180:183], v146 offset:2048
	ds_read_b128 v[184:187], v146 offset:3072
	ds_read_b128 v[188:191], v146 offset:4096
	ds_read_b128 v[192:195], v146 offset:5120
	ds_read_b128 v[196:199], v146 offset:6144
	ds_read_b128 v[200:203], v146 offset:7168
	s_add_u32 s6, s8, 0xfff80080
	s_addc_u32 s7, s9, -1
	s_add_i32 s29, 0, 0x10000
	s_cmp_eq_u32 s28, 28
	s_cselect_b32 s17, s13, s7
	s_cselect_b32 s16, s12, s6
	s_cselect_b32 s7, s15, s27
	s_cselect_b32 s6, s14, s26
	s_add_i32 s53, 0, 0x14000
	s_mov_b32 m0, s66
	global_load_lds_dwordx4 v2, s[8:9]
	s_mov_b32 m0, s67
	v_mov_b32_e32 v133, v3
	global_load_lds_dwordx4 v132, s[8:9]
	s_waitcnt vmcnt(8)
	s_waitcnt lgkmcnt(0)
	s_barrier
	s_setprio 1
	s_waitcnt lgkmcnt(0)
	v_mfma_f32_16x16x32_f16 v[4:7], v[138:141], v[172:175], v[4:7]
	v_mfma_f32_16x16x32_f16 v[4:7], v[142:145], v[176:179], v[4:7]
	v_mfma_f32_16x16x32_f16 v[8:11], v[152:155], v[176:179], v[8:11]
	v_mfma_f32_16x16x32_f16 v[8:11], v[148:151], v[172:175], v[8:11]
	v_mfma_f32_16x16x32_f16 v[16:19], v[148:151], v[180:183], v[16:19]
	v_mfma_f32_16x16x32_f16 v[16:19], v[152:155], v[184:187], v[16:19]
	v_mfma_f32_16x16x32_f16 v[12:15], v[142:145], v[184:187], v[12:15]
	v_mfma_f32_16x16x32_f16 v[12:15], v[138:141], v[180:183], v[12:15]
	v_mfma_f32_16x16x32_f16 v[20:23], v[138:141], v[188:191], v[20:23]
	v_mfma_f32_16x16x32_f16 v[20:23], v[142:145], v[192:195], v[20:23]
	v_mfma_f32_16x16x32_f16 v[24:27], v[152:155], v[192:195], v[24:27]
	v_mfma_f32_16x16x32_f16 v[24:27], v[148:151], v[188:191], v[24:27]
	v_mfma_f32_16x16x32_f16 v[32:35], v[148:151], v[196:199], v[32:35]
	v_mfma_f32_16x16x32_f16 v[32:35], v[152:155], v[200:203], v[32:35]
	v_mfma_f32_16x16x32_f16 v[28:31], v[142:145], v[200:203], v[28:31]
	v_mfma_f32_16x16x32_f16 v[28:31], v[138:141], v[196:199], v[28:31]
	s_setprio 0
	s_setprio 1
	v_mfma_f32_16x16x32_f16 v[36:39], v[156:159], v[172:175], v[36:39]
	v_mfma_f32_16x16x32_f16 v[36:39], v[160:163], v[176:179], v[36:39]
	v_mfma_f32_16x16x32_f16 v[40:43], v[168:171], v[176:179], v[40:43]
	v_mfma_f32_16x16x32_f16 v[40:43], v[164:167], v[172:175], v[40:43]
	v_mfma_f32_16x16x32_f16 v[48:51], v[164:167], v[180:183], v[48:51]
	v_mfma_f32_16x16x32_f16 v[48:51], v[168:171], v[184:187], v[48:51]
	v_mfma_f32_16x16x32_f16 v[44:47], v[160:163], v[184:187], v[44:47]
	v_mfma_f32_16x16x32_f16 v[44:47], v[156:159], v[180:183], v[44:47]
	v_mfma_f32_16x16x32_f16 v[52:55], v[156:159], v[188:191], v[52:55]
	v_mfma_f32_16x16x32_f16 v[52:55], v[160:163], v[192:195], v[52:55]
	v_mfma_f32_16x16x32_f16 v[56:59], v[168:171], v[192:195], v[56:59]
	v_mfma_f32_16x16x32_f16 v[56:59], v[164:167], v[188:191], v[56:59]
	v_mfma_f32_16x16x32_f16 v[64:67], v[164:167], v[196:199], v[64:67]
	v_mfma_f32_16x16x32_f16 v[64:67], v[168:171], v[200:203], v[64:67]
	s_setprio 2
	s_barrier
	v_mfma_f32_16x16x32_f16 v[60:63], v[160:163], v[200:203], v[60:63]
	v_mfma_f32_16x16x32_f16 v[60:63], v[156:159], v[196:199], v[60:63]
	s_setprio 0
	s_add_i32 s29, s29, s38
	s_mov_b32 m0, s29
	ds_read_b128 v[172:175], v146 offset:16384
	ds_read_b128 v[176:179], v146 offset:17408
	ds_read_b128 v[180:183], v146 offset:18432
	ds_read_b128 v[184:187], v146 offset:19456
	ds_read_b128 v[188:191], v146 offset:20480
	ds_read_b128 v[192:195], v146 offset:21504
	ds_read_b128 v[196:199], v146 offset:22528
	ds_read_b128 v[200:203], v146 offset:23552
	global_load_lds_dwordx4 v136, s[6:7]
	s_add_i32 m0, s29, 0x2000
	s_add_u32 s40, s6, 0x80000
	s_addc_u32 s41, s7, 0
	s_add_i32 s29, s53, s38
	global_load_lds_dwordx4 v134, s[6:7]
	s_mov_b32 m0, s29
	v_mov_b32_e32 v137, v3
	global_load_lds_dwordx4 v136, s[40:41]
	s_add_i32 m0, s29, 0x2000
	v_mov_b32_e32 v135, v3
	global_load_lds_dwordx4 v134, s[40:41]
	s_mov_b32 m0, s58
	s_nop 0
	global_load_lds_dwordx4 v2, s[16:17]
	s_mov_b32 m0, s59
	s_nop 0
	global_load_lds_dwordx4 v132, s[16:17]
	s_waitcnt vmcnt(8)
	s_waitcnt lgkmcnt(0)
	s_add_u32 s88, s6, s86
	s_addc_u32 s89, s7, s87
	s_add_u32 s90, s16, s86
	s_addc_u32 s91, s17, s87
	s_barrier
	s_setprio 1
	s_waitcnt lgkmcnt(0)
	v_mfma_f32_16x16x32_f16 v[68:71], v[138:141], v[172:175], v[68:71]
	v_mfma_f32_16x16x32_f16 v[68:71], v[142:145], v[176:179], v[68:71]
	v_mfma_f32_16x16x32_f16 v[72:75], v[152:155], v[176:179], v[72:75]
	v_mfma_f32_16x16x32_f16 v[72:75], v[148:151], v[172:175], v[72:75]
	v_mfma_f32_16x16x32_f16 v[80:83], v[148:151], v[180:183], v[80:83]
	v_mfma_f32_16x16x32_f16 v[80:83], v[152:155], v[184:187], v[80:83]
	v_mfma_f32_16x16x32_f16 v[76:79], v[142:145], v[184:187], v[76:79]
	v_mfma_f32_16x16x32_f16 v[76:79], v[138:141], v[180:183], v[76:79]
	v_mfma_f32_16x16x32_f16 v[84:87], v[138:141], v[188:191], v[84:87]
	v_mfma_f32_16x16x32_f16 v[84:87], v[142:145], v[192:195], v[84:87]
	v_mfma_f32_16x16x32_f16 v[88:91], v[152:155], v[192:195], v[88:91]
	v_mfma_f32_16x16x32_f16 v[88:91], v[148:151], v[188:191], v[88:91]
	v_mfma_f32_16x16x32_f16 v[96:99], v[148:151], v[196:199], v[96:99]
	v_mfma_f32_16x16x32_f16 v[96:99], v[152:155], v[200:203], v[96:99]
	v_mfma_f32_16x16x32_f16 v[92:95], v[142:145], v[200:203], v[92:95]
	v_mfma_f32_16x16x32_f16 v[92:95], v[138:141], v[196:199], v[92:95]
	s_setprio 0
	s_setprio 1
	v_mfma_f32_16x16x32_f16 v[100:103], v[156:159], v[172:175], v[100:103]
	v_mfma_f32_16x16x32_f16 v[100:103], v[160:163], v[176:179], v[100:103]
	v_mfma_f32_16x16x32_f16 v[104:107], v[168:171], v[176:179], v[104:107]
	v_mfma_f32_16x16x32_f16 v[104:107], v[164:167], v[172:175], v[104:107]
	v_mfma_f32_16x16x32_f16 v[112:115], v[164:167], v[180:183], v[112:115]
	v_mfma_f32_16x16x32_f16 v[112:115], v[168:171], v[184:187], v[112:115]
	v_mfma_f32_16x16x32_f16 v[108:111], v[160:163], v[184:187], v[108:111]
	v_mfma_f32_16x16x32_f16 v[108:111], v[156:159], v[180:183], v[108:111]
	v_mfma_f32_16x16x32_f16 v[116:119], v[156:159], v[188:191], v[116:119]
	v_mfma_f32_16x16x32_f16 v[116:119], v[160:163], v[192:195], v[116:119]
	v_mfma_f32_16x16x32_f16 v[120:123], v[168:171], v[192:195], v[120:123]
	v_mfma_f32_16x16x32_f16 v[120:123], v[164:167], v[188:191], v[120:123]
	v_mfma_f32_16x16x32_f16 v[128:131], v[164:167], v[196:199], v[128:131]
	v_mfma_f32_16x16x32_f16 v[128:131], v[168:171], v[200:203], v[128:131]
	s_setprio 2
	s_barrier
	v_mfma_f32_16x16x32_f16 v[124:127], v[160:163], v[200:203], v[124:127]
	v_mfma_f32_16x16x32_f16 v[124:127], v[156:159], v[196:199], v[124:127]
	s_setprio 0
	s_add_i32 s29, 0, 0x18000
	s_add_i32 s40, 0, 0x1c000
	ds_read_b128 v[138:141], v240 offset:32768
	ds_read_b128 v[142:145], v240 offset:33792
	ds_read_b128 v[148:151], v240 offset:34816
	ds_read_b128 v[152:155], v240 offset:35840
	ds_read_b128 v[156:159], v240 offset:49152
	ds_read_b128 v[160:163], v240 offset:50176
	ds_read_b128 v[164:167], v240 offset:51200
	ds_read_b128 v[168:171], v240 offset:52224
	s_add_u32 s16, s16, 0x80000
	s_addc_u32 s17, s17, 0
	s_mov_b32 m0, s60
	ds_read_b128 v[172:175], v146 offset:32768
	ds_read_b128 v[176:179], v146 offset:33792
	ds_read_b128 v[180:183], v146 offset:34816
	ds_read_b128 v[184:187], v146 offset:35840
	ds_read_b128 v[188:191], v146 offset:36864
	ds_read_b128 v[192:195], v146 offset:37888
	ds_read_b128 v[196:199], v146 offset:38912
	ds_read_b128 v[200:203], v146 offset:39936
	global_load_lds_dwordx4 v2, s[16:17]
	s_mov_b32 m0, s61
	s_nop 0
	global_load_lds_dwordx4 v132, s[16:17]
	s_waitcnt vmcnt(8)
	s_waitcnt lgkmcnt(0)
	s_barrier
	s_setprio 1
	s_waitcnt lgkmcnt(0)
	v_mfma_f32_16x16x32_f16 v[4:7], v[138:141], v[172:175], v[4:7]
	v_mfma_f32_16x16x32_f16 v[4:7], v[142:145], v[176:179], v[4:7]
	v_mfma_f32_16x16x32_f16 v[8:11], v[152:155], v[176:179], v[8:11]
	v_mfma_f32_16x16x32_f16 v[8:11], v[148:151], v[172:175], v[8:11]
	v_mfma_f32_16x16x32_f16 v[16:19], v[148:151], v[180:183], v[16:19]
	v_mfma_f32_16x16x32_f16 v[16:19], v[152:155], v[184:187], v[16:19]
	v_mfma_f32_16x16x32_f16 v[12:15], v[142:145], v[184:187], v[12:15]
	v_mfma_f32_16x16x32_f16 v[12:15], v[138:141], v[180:183], v[12:15]
	v_mfma_f32_16x16x32_f16 v[20:23], v[138:141], v[188:191], v[20:23]
	v_mfma_f32_16x16x32_f16 v[20:23], v[142:145], v[192:195], v[20:23]
	v_mfma_f32_16x16x32_f16 v[24:27], v[152:155], v[192:195], v[24:27]
	v_mfma_f32_16x16x32_f16 v[24:27], v[148:151], v[188:191], v[24:27]
	v_mfma_f32_16x16x32_f16 v[32:35], v[148:151], v[196:199], v[32:35]
	v_mfma_f32_16x16x32_f16 v[32:35], v[152:155], v[200:203], v[32:35]
	v_mfma_f32_16x16x32_f16 v[28:31], v[142:145], v[200:203], v[28:31]
	v_mfma_f32_16x16x32_f16 v[28:31], v[138:141], v[196:199], v[28:31]
	s_setprio 0
	s_setprio 1
	v_mfma_f32_16x16x32_f16 v[36:39], v[156:159], v[172:175], v[36:39]
	v_mfma_f32_16x16x32_f16 v[36:39], v[160:163], v[176:179], v[36:39]
	v_mfma_f32_16x16x32_f16 v[40:43], v[168:171], v[176:179], v[40:43]
	v_mfma_f32_16x16x32_f16 v[40:43], v[164:167], v[172:175], v[40:43]
	v_mfma_f32_16x16x32_f16 v[48:51], v[164:167], v[180:183], v[48:51]
	v_mfma_f32_16x16x32_f16 v[48:51], v[168:171], v[184:187], v[48:51]
	v_mfma_f32_16x16x32_f16 v[44:47], v[160:163], v[184:187], v[44:47]
	v_mfma_f32_16x16x32_f16 v[44:47], v[156:159], v[180:183], v[44:47]
	v_mfma_f32_16x16x32_f16 v[52:55], v[156:159], v[188:191], v[52:55]
	v_mfma_f32_16x16x32_f16 v[52:55], v[160:163], v[192:195], v[52:55]
	v_mfma_f32_16x16x32_f16 v[56:59], v[168:171], v[192:195], v[56:59]
	v_mfma_f32_16x16x32_f16 v[56:59], v[164:167], v[188:191], v[56:59]
	v_mfma_f32_16x16x32_f16 v[64:67], v[164:167], v[196:199], v[64:67]
	v_mfma_f32_16x16x32_f16 v[64:67], v[168:171], v[200:203], v[64:67]
	s_setprio 2
	s_barrier
	v_mfma_f32_16x16x32_f16 v[60:63], v[160:163], v[200:203], v[60:63]
	v_mfma_f32_16x16x32_f16 v[60:63], v[156:159], v[196:199], v[60:63]
	s_setprio 0
	s_add_i32 s16, s29, s38
	s_mov_b32 m0, s16
	ds_read_b128 v[172:175], v146 offset:49152
	ds_read_b128 v[176:179], v146 offset:50176
	ds_read_b128 v[180:183], v146 offset:51200
	ds_read_b128 v[184:187], v146 offset:52224
	ds_read_b128 v[188:191], v146 offset:53248
	ds_read_b128 v[192:195], v146 offset:54272
	ds_read_b128 v[196:199], v146 offset:55296
	ds_read_b128 v[200:203], v146 offset:56320
	global_load_lds_dwordx4 v136, s[88:89]
	s_add_i32 m0, s16, 0x2000
	s_add_u32 s6, s6, 0x80080
	s_addc_u32 s7, s7, 0
	s_add_i32 s16, s40, s38
	global_load_lds_dwordx4 v134, s[88:89]
	s_mov_b32 m0, s16
	s_nop 0
	global_load_lds_dwordx4 v136, s[6:7]
	s_add_i32 m0, s16, 0x2000
	s_nop 0
	global_load_lds_dwordx4 v134, s[6:7]
	s_mov_b32 m0, s64
	s_nop 0
	global_load_lds_dwordx4 v2, s[90:91]
	s_mov_b32 m0, s65
	s_nop 0
	global_load_lds_dwordx4 v132, s[90:91]
	s_waitcnt vmcnt(8)
	s_waitcnt lgkmcnt(0)
	s_barrier
	s_setprio 1
	s_waitcnt lgkmcnt(0)
	v_mfma_f32_16x16x32_f16 v[68:71], v[138:141], v[172:175], v[68:71]
	v_mfma_f32_16x16x32_f16 v[68:71], v[142:145], v[176:179], v[68:71]
	v_mfma_f32_16x16x32_f16 v[72:75], v[152:155], v[176:179], v[72:75]
	v_mfma_f32_16x16x32_f16 v[72:75], v[148:151], v[172:175], v[72:75]
	v_mfma_f32_16x16x32_f16 v[80:83], v[148:151], v[180:183], v[80:83]
	v_mfma_f32_16x16x32_f16 v[80:83], v[152:155], v[184:187], v[80:83]
	v_mfma_f32_16x16x32_f16 v[76:79], v[142:145], v[184:187], v[76:79]
	v_mfma_f32_16x16x32_f16 v[76:79], v[138:141], v[180:183], v[76:79]
	v_mfma_f32_16x16x32_f16 v[84:87], v[138:141], v[188:191], v[84:87]
	v_mfma_f32_16x16x32_f16 v[84:87], v[142:145], v[192:195], v[84:87]
	v_mfma_f32_16x16x32_f16 v[88:91], v[152:155], v[192:195], v[88:91]
	v_mfma_f32_16x16x32_f16 v[88:91], v[148:151], v[188:191], v[88:91]
	v_mfma_f32_16x16x32_f16 v[96:99], v[148:151], v[196:199], v[96:99]
	v_mfma_f32_16x16x32_f16 v[96:99], v[152:155], v[200:203], v[96:99]
	v_mfma_f32_16x16x32_f16 v[92:95], v[142:145], v[200:203], v[92:95]
	v_mfma_f32_16x16x32_f16 v[92:95], v[138:141], v[196:199], v[92:95]
	s_setprio 0
	s_setprio 1
	v_mfma_f32_16x16x32_f16 v[100:103], v[156:159], v[172:175], v[100:103]
	v_mfma_f32_16x16x32_f16 v[100:103], v[160:163], v[176:179], v[100:103]
	v_mfma_f32_16x16x32_f16 v[104:107], v[168:171], v[176:179], v[104:107]
	v_mfma_f32_16x16x32_f16 v[104:107], v[164:167], v[172:175], v[104:107]
	v_mfma_f32_16x16x32_f16 v[112:115], v[164:167], v[180:183], v[112:115]
	v_mfma_f32_16x16x32_f16 v[112:115], v[168:171], v[184:187], v[112:115]
	v_mfma_f32_16x16x32_f16 v[108:111], v[160:163], v[184:187], v[108:111]
	v_mfma_f32_16x16x32_f16 v[108:111], v[156:159], v[180:183], v[108:111]
	v_mfma_f32_16x16x32_f16 v[116:119], v[156:159], v[188:191], v[116:119]
	v_mfma_f32_16x16x32_f16 v[116:119], v[160:163], v[192:195], v[116:119]
	v_mfma_f32_16x16x32_f16 v[120:123], v[168:171], v[192:195], v[120:123]
	v_mfma_f32_16x16x32_f16 v[120:123], v[164:167], v[188:191], v[120:123]
	v_mfma_f32_16x16x32_f16 v[128:131], v[164:167], v[196:199], v[128:131]
	v_mfma_f32_16x16x32_f16 v[128:131], v[168:171], v[200:203], v[128:131]
	s_setprio 2
	s_barrier
	v_mfma_f32_16x16x32_f16 v[124:127], v[160:163], v[200:203], v[124:127]
	v_mfma_f32_16x16x32_f16 v[124:127], v[156:159], v[196:199], v[124:127]
	s_setprio 0
	s_add_i32 s28, s28, 2
	s_add_u32 s8, s8, 0x100
	s_addc_u32 s9, s9, 0
	s_add_u32 s26, s26, 0x100
	s_addc_u32 s27, s27, 0
	s_cmp_gt_u32 s28, 29
	s_cbranch_scc0 .LBB0_532
	s_and_b64 vcc, exec, s[50:51]
	s_cbranch_vccz .LBB0_535
	s_barrier

.LBB0_645:
	s_waitcnt lgkmcnt(0)
	ds_read_b128 v[132:135], v240
	ds_read_b128 v[136:139], v240 offset:1024
	ds_read_b128 v[140:143], v240 offset:2048
	ds_read_b128 v[144:147], v240 offset:3072
	ds_read_b128 v[148:151], v240 offset:16384
	ds_read_b128 v[152:155], v240 offset:17408
	ds_read_b128 v[156:159], v240 offset:18432
	ds_read_b128 v[160:163], v240 offset:19456
	ds_read_b128 v[164:167], v231
	ds_read_b128 v[168:171], v231 offset:1024
	ds_read_b128 v[172:175], v231 offset:2048
	ds_read_b128 v[176:179], v231 offset:3072
	ds_read_b128 v[180:183], v231 offset:4096
	ds_read_b128 v[184:187], v231 offset:5120
	ds_read_b128 v[194:197], v231 offset:6144
	ds_read_b128 v[198:201], v231 offset:7168
	s_cmpk_lg_i32 s28, 0x56
	s_cselect_b64 s[16:17], -1, 0
	s_cmpk_eq_i32 s28, 0x56
	s_mov_b64 s[26:27], s[12:13]
	s_cbranch_scc1 .LBB0_647
	s_add_i32 s38, s28, 2
	s_lshl_b64 s[26:27], s[38:39], 7
	s_sub_u32 s26, 0, s26
	s_subb_u32 s27, 0, s27
	s_add_u32 s26, s6, s26
	s_addc_u32 s27, s7, s27

.LBB0_649:
	s_or_b32 s38, s28, 1
	s_lshl_b64 s[42:43], s[38:39], 7
	s_sub_u32 s38, 0, s42
	s_subb_u32 s42, 0, s43
	s_add_u32 s38, s6, s38
	s_addc_u32 s43, s7, s42
	s_add_i32 s71, 0, 0x10000
	s_add_i32 s72, 0, 0x14000
	s_add_u32 s42, s38, 0x160000
	s_mov_b32 m0, s64
	s_addc_u32 s43, s43, 0
	global_load_lds_dwordx4 v2, s[42:43]
	s_mov_b32 m0, s65
	v_mov_b32_e32 v189, v3
	global_load_lds_dwordx4 v188, s[42:43]
	s_waitcnt vmcnt(8)
	s_waitcnt lgkmcnt(0)
	s_barrier
	s_setprio 1
	s_waitcnt lgkmcnt(0)
	v_mfma_f32_16x16x32_bf16 v[4:7], v[132:135], v[164:167], v[4:7]
	v_mfma_f32_16x16x32_bf16 v[4:7], v[136:139], v[168:171], v[4:7]
	v_mfma_f32_16x16x32_bf16 v[8:11], v[144:147], v[168:171], v[8:11]
	v_mfma_f32_16x16x32_bf16 v[8:11], v[140:143], v[164:167], v[8:11]
	v_mfma_f32_16x16x32_bf16 v[16:19], v[140:143], v[172:175], v[16:19]
	v_mfma_f32_16x16x32_bf16 v[16:19], v[144:147], v[176:179], v[16:19]
	v_mfma_f32_16x16x32_bf16 v[12:15], v[136:139], v[176:179], v[12:15]
	v_mfma_f32_16x16x32_bf16 v[12:15], v[132:135], v[172:175], v[12:15]
	v_mfma_f32_16x16x32_bf16 v[20:23], v[132:135], v[180:183], v[20:23]
	v_mfma_f32_16x16x32_bf16 v[20:23], v[136:139], v[184:187], v[20:23]
	v_mfma_f32_16x16x32_bf16 v[24:27], v[144:147], v[184:187], v[24:27]
	v_mfma_f32_16x16x32_bf16 v[24:27], v[140:143], v[180:183], v[24:27]
	v_mfma_f32_16x16x32_bf16 v[32:35], v[140:143], v[194:197], v[32:35]
	v_mfma_f32_16x16x32_bf16 v[32:35], v[144:147], v[198:201], v[32:35]
	v_mfma_f32_16x16x32_bf16 v[28:31], v[136:139], v[198:201], v[28:31]
	v_mfma_f32_16x16x32_bf16 v[28:31], v[132:135], v[194:197], v[28:31]
	s_setprio 0
	s_setprio 1
	v_mfma_f32_16x16x32_bf16 v[36:39], v[148:151], v[164:167], v[36:39]
	v_mfma_f32_16x16x32_bf16 v[36:39], v[152:155], v[168:171], v[36:39]
	v_mfma_f32_16x16x32_bf16 v[40:43], v[160:163], v[168:171], v[40:43]
	v_mfma_f32_16x16x32_bf16 v[40:43], v[156:159], v[164:167], v[40:43]
	v_mfma_f32_16x16x32_bf16 v[48:51], v[156:159], v[172:175], v[48:51]
	v_mfma_f32_16x16x32_bf16 v[48:51], v[160:163], v[176:179], v[48:51]
	v_mfma_f32_16x16x32_bf16 v[44:47], v[152:155], v[176:179], v[44:47]
	v_mfma_f32_16x16x32_bf16 v[44:47], v[148:151], v[172:175], v[44:47]
	v_mfma_f32_16x16x32_bf16 v[52:55], v[148:151], v[180:183], v[52:55]
	v_mfma_f32_16x16x32_bf16 v[52:55], v[152:155], v[184:187], v[52:55]
	v_mfma_f32_16x16x32_bf16 v[56:59], v[160:163], v[184:187], v[56:59]
	v_mfma_f32_16x16x32_bf16 v[56:59], v[156:159], v[180:183], v[56:59]
	v_mfma_f32_16x16x32_bf16 v[64:67], v[156:159], v[194:197], v[64:67]
	v_mfma_f32_16x16x32_bf16 v[64:67], v[160:163], v[198:201], v[64:67]
	s_setprio 2
	s_barrier
	v_mfma_f32_16x16x32_bf16 v[60:63], v[152:155], v[198:201], v[60:63]
	v_mfma_f32_16x16x32_bf16 v[60:63], v[148:151], v[194:197], v[60:63]
	s_setprio 0
	s_add_i32 s38, s71, s54
	s_mov_b32 m0, s38
	ds_read_b128 v[164:167], v231 offset:16384
	ds_read_b128 v[168:171], v231 offset:17408
	ds_read_b128 v[172:175], v231 offset:18432
	ds_read_b128 v[176:179], v231 offset:19456
	ds_read_b128 v[180:183], v231 offset:20480
	ds_read_b128 v[184:187], v231 offset:21504
	ds_read_b128 v[194:197], v231 offset:22528
	ds_read_b128 v[198:201], v231 offset:23552
	global_load_lds_dwordx4 v192, s[16:17]
	s_add_i32 m0, s38, 0x2000
	s_add_u32 s42, s16, 0x160000
	s_addc_u32 s43, s17, 0
	s_add_i32 s38, s72, s54
	global_load_lds_dwordx4 v190, s[16:17]
	s_mov_b32 m0, s38
	v_mov_b32_e32 v193, v3
	global_load_lds_dwordx4 v192, s[42:43]
	s_add_i32 m0, s38, 0x2000
	v_mov_b32_e32 v191, v3
	global_load_lds_dwordx4 v190, s[42:43]
	s_mov_b32 m0, s55
	s_nop 0
	global_load_lds_dwordx4 v2, s[26:27]
	s_mov_b32 m0, s56
	s_nop 0
	global_load_lds_dwordx4 v188, s[26:27]
	s_waitcnt vmcnt(8)
	s_waitcnt lgkmcnt(0)
	s_add_u32 s88, s16, s4
	s_addc_u32 s89, s17, s5
	s_add_u32 s90, s26, s4
	s_addc_u32 s91, s27, s5
	s_barrier
	s_setprio 1
	s_waitcnt lgkmcnt(0)
	v_mfma_f32_16x16x32_bf16 v[68:71], v[132:135], v[164:167], v[68:71]
	v_mfma_f32_16x16x32_bf16 v[68:71], v[136:139], v[168:171], v[68:71]
	v_mfma_f32_16x16x32_bf16 v[72:75], v[144:147], v[168:171], v[72:75]
	v_mfma_f32_16x16x32_bf16 v[72:75], v[140:143], v[164:167], v[72:75]
	v_mfma_f32_16x16x32_bf16 v[80:83], v[140:143], v[172:175], v[80:83]
	v_mfma_f32_16x16x32_bf16 v[80:83], v[144:147], v[176:179], v[80:83]
	v_mfma_f32_16x16x32_bf16 v[76:79], v[136:139], v[176:179], v[76:79]
	v_mfma_f32_16x16x32_bf16 v[76:79], v[132:135], v[172:175], v[76:79]
	v_mfma_f32_16x16x32_bf16 v[84:87], v[132:135], v[180:183], v[84:87]
	v_mfma_f32_16x16x32_bf16 v[84:87], v[136:139], v[184:187], v[84:87]
	v_mfma_f32_16x16x32_bf16 v[88:91], v[144:147], v[184:187], v[88:91]
	v_mfma_f32_16x16x32_bf16 v[88:91], v[140:143], v[180:183], v[88:91]
	v_mfma_f32_16x16x32_bf16 v[96:99], v[140:143], v[194:197], v[96:99]
	v_mfma_f32_16x16x32_bf16 v[96:99], v[144:147], v[198:201], v[96:99]
	v_mfma_f32_16x16x32_bf16 v[92:95], v[136:139], v[198:201], v[92:95]
	v_mfma_f32_16x16x32_bf16 v[92:95], v[132:135], v[194:197], v[92:95]
	s_setprio 0
	s_setprio 1
	v_mfma_f32_16x16x32_bf16 v[100:103], v[148:151], v[164:167], v[100:103]
	v_mfma_f32_16x16x32_bf16 v[100:103], v[152:155], v[168:171], v[100:103]
	v_mfma_f32_16x16x32_bf16 v[104:107], v[160:163], v[168:171], v[104:107]
	v_mfma_f32_16x16x32_bf16 v[104:107], v[156:159], v[164:167], v[104:107]
	v_mfma_f32_16x16x32_bf16 v[112:115], v[156:159], v[172:175], v[112:115]
	v_mfma_f32_16x16x32_bf16 v[112:115], v[160:163], v[176:179], v[112:115]
	v_mfma_f32_16x16x32_bf16 v[108:111], v[152:155], v[176:179], v[108:111]
	v_mfma_f32_16x16x32_bf16 v[108:111], v[148:151], v[172:175], v[108:111]
	v_mfma_f32_16x16x32_bf16 v[116:119], v[148:151], v[180:183], v[116:119]
	v_mfma_f32_16x16x32_bf16 v[116:119], v[152:155], v[184:187], v[116:119]
	v_mfma_f32_16x16x32_bf16 v[120:123], v[160:163], v[184:187], v[120:123]
	v_mfma_f32_16x16x32_bf16 v[120:123], v[156:159], v[180:183], v[120:123]
	v_mfma_f32_16x16x32_bf16 v[128:131], v[156:159], v[194:197], v[128:131]
	v_mfma_f32_16x16x32_bf16 v[128:131], v[160:163], v[198:201], v[128:131]
	s_setprio 2
	s_barrier
	v_mfma_f32_16x16x32_bf16 v[124:127], v[152:155], v[198:201], v[124:127]
	v_mfma_f32_16x16x32_bf16 v[124:127], v[148:151], v[194:197], v[124:127]
	s_setprio 0
	s_add_i32 s38, 0, 0x18000
	s_add_i32 s42, 0, 0x1c000
	ds_read_b128 v[132:135], v240 offset:32768
	ds_read_b128 v[136:139], v240 offset:33792
	ds_read_b128 v[140:143], v240 offset:34816
	ds_read_b128 v[144:147], v240 offset:35840
	ds_read_b128 v[148:151], v240 offset:49152
	ds_read_b128 v[152:155], v240 offset:50176
	ds_read_b128 v[156:159], v240 offset:51200
	ds_read_b128 v[160:163], v240 offset:52224
	s_add_u32 s26, s26, 0x160000
	s_addc_u32 s27, s27, 0
	s_mov_b32 m0, s57
	ds_read_b128 v[164:167], v231 offset:32768
	ds_read_b128 v[168:171], v231 offset:33792
	ds_read_b128 v[172:175], v231 offset:34816
	ds_read_b128 v[176:179], v231 offset:35840
	ds_read_b128 v[180:183], v231 offset:36864
	ds_read_b128 v[184:187], v231 offset:37888
	ds_read_b128 v[194:197], v231 offset:38912
	ds_read_b128 v[198:201], v231 offset:39936
	global_load_lds_dwordx4 v2, s[26:27]
	s_mov_b32 m0, s58
	s_nop 0
	global_load_lds_dwordx4 v188, s[26:27]
	s_waitcnt vmcnt(8)
	s_waitcnt lgkmcnt(0)
	s_barrier
	s_setprio 1
	s_waitcnt lgkmcnt(0)
	v_mfma_f32_16x16x32_bf16 v[4:7], v[132:135], v[164:167], v[4:7]
	v_mfma_f32_16x16x32_bf16 v[4:7], v[136:139], v[168:171], v[4:7]
	v_mfma_f32_16x16x32_bf16 v[8:11], v[144:147], v[168:171], v[8:11]
	v_mfma_f32_16x16x32_bf16 v[8:11], v[140:143], v[164:167], v[8:11]
	v_mfma_f32_16x16x32_bf16 v[16:19], v[140:143], v[172:175], v[16:19]
	v_mfma_f32_16x16x32_bf16 v[16:19], v[144:147], v[176:179], v[16:19]
	v_mfma_f32_16x16x32_bf16 v[12:15], v[136:139], v[176:179], v[12:15]
	v_mfma_f32_16x16x32_bf16 v[12:15], v[132:135], v[172:175], v[12:15]
	v_mfma_f32_16x16x32_bf16 v[20:23], v[132:135], v[180:183], v[20:23]
	v_mfma_f32_16x16x32_bf16 v[20:23], v[136:139], v[184:187], v[20:23]
	v_mfma_f32_16x16x32_bf16 v[24:27], v[144:147], v[184:187], v[24:27]
	v_mfma_f32_16x16x32_bf16 v[24:27], v[140:143], v[180:183], v[24:27]
	v_mfma_f32_16x16x32_bf16 v[32:35], v[140:143], v[194:197], v[32:35]
	v_mfma_f32_16x16x32_bf16 v[32:35], v[144:147], v[198:201], v[32:35]
	v_mfma_f32_16x16x32_bf16 v[28:31], v[136:139], v[198:201], v[28:31]
	v_mfma_f32_16x16x32_bf16 v[28:31], v[132:135], v[194:197], v[28:31]
	s_setprio 0
	s_setprio 1
	v_mfma_f32_16x16x32_bf16 v[36:39], v[148:151], v[164:167], v[36:39]
	v_mfma_f32_16x16x32_bf16 v[36:39], v[152:155], v[168:171], v[36:39]
	v_mfma_f32_16x16x32_bf16 v[40:43], v[160:163], v[168:171], v[40:43]
	v_mfma_f32_16x16x32_bf16 v[40:43], v[156:159], v[164:167], v[40:43]
	v_mfma_f32_16x16x32_bf16 v[48:51], v[156:159], v[172:175], v[48:51]
	v_mfma_f32_16x16x32_bf16 v[48:51], v[160:163], v[176:179], v[48:51]
	v_mfma_f32_16x16x32_bf16 v[44:47], v[152:155], v[176:179], v[44:47]
	v_mfma_f32_16x16x32_bf16 v[44:47], v[148:151], v[172:175], v[44:47]
	v_mfma_f32_16x16x32_bf16 v[52:55], v[148:151], v[180:183], v[52:55]
	v_mfma_f32_16x16x32_bf16 v[52:55], v[152:155], v[184:187], v[52:55]
	v_mfma_f32_16x16x32_bf16 v[56:59], v[160:163], v[184:187], v[56:59]
	v_mfma_f32_16x16x32_bf16 v[56:59], v[156:159], v[180:183], v[56:59]
	v_mfma_f32_16x16x32_bf16 v[64:67], v[156:159], v[194:197], v[64:67]
	v_mfma_f32_16x16x32_bf16 v[64:67], v[160:163], v[198:201], v[64:67]
	s_setprio 2
	s_barrier
	v_mfma_f32_16x16x32_bf16 v[60:63], v[152:155], v[198:201], v[60:63]
	v_mfma_f32_16x16x32_bf16 v[60:63], v[148:151], v[194:197], v[60:63]
	s_setprio 0
	s_add_i32 s26, s38, s54
	s_mov_b32 m0, s26
	ds_read_b128 v[164:167], v231 offset:49152
	ds_read_b128 v[168:171], v231 offset:50176
	ds_read_b128 v[172:175], v231 offset:51200
	ds_read_b128 v[176:179], v231 offset:52224
	ds_read_b128 v[180:183], v231 offset:53248
	ds_read_b128 v[184:187], v231 offset:54272
	ds_read_b128 v[194:197], v231 offset:55296
	ds_read_b128 v[198:201], v231 offset:56320
	global_load_lds_dwordx4 v192, s[88:89]
	s_add_i32 m0, s26, 0x2000
	s_add_u32 s16, s16, 0x15ff80
	s_addc_u32 s17, s17, 0
	s_add_i32 s26, s42, s54
	global_load_lds_dwordx4 v190, s[88:89]
	s_mov_b32 m0, s26
	s_nop 0
	global_load_lds_dwordx4 v192, s[16:17]
	s_add_i32 m0, s26, 0x2000
	s_nop 0
	global_load_lds_dwordx4 v190, s[16:17]
	s_mov_b32 m0, s62
	s_nop 0
	global_load_lds_dwordx4 v2, s[90:91]
	s_mov_b32 m0, s63
	s_nop 0
	global_load_lds_dwordx4 v188, s[90:91]
	s_waitcnt vmcnt(8)
	s_waitcnt lgkmcnt(0)
	s_barrier
	s_setprio 1
	s_waitcnt lgkmcnt(0)
	v_mfma_f32_16x16x32_bf16 v[68:71], v[132:135], v[164:167], v[68:71]
	v_mfma_f32_16x16x32_bf16 v[68:71], v[136:139], v[168:171], v[68:71]
	v_mfma_f32_16x16x32_bf16 v[72:75], v[144:147], v[168:171], v[72:75]
	v_mfma_f32_16x16x32_bf16 v[72:75], v[140:143], v[164:167], v[72:75]
	v_mfma_f32_16x16x32_bf16 v[80:83], v[140:143], v[172:175], v[80:83]
	v_mfma_f32_16x16x32_bf16 v[80:83], v[144:147], v[176:179], v[80:83]
	v_mfma_f32_16x16x32_bf16 v[76:79], v[136:139], v[176:179], v[76:79]
	v_mfma_f32_16x16x32_bf16 v[76:79], v[132:135], v[172:175], v[76:79]
	v_mfma_f32_16x16x32_bf16 v[84:87], v[132:135], v[180:183], v[84:87]
	v_mfma_f32_16x16x32_bf16 v[84:87], v[136:139], v[184:187], v[84:87]
	v_mfma_f32_16x16x32_bf16 v[88:91], v[144:147], v[184:187], v[88:91]
	v_mfma_f32_16x16x32_bf16 v[88:91], v[140:143], v[180:183], v[88:91]
	v_mfma_f32_16x16x32_bf16 v[96:99], v[140:143], v[194:197], v[96:99]
	v_mfma_f32_16x16x32_bf16 v[96:99], v[144:147], v[198:201], v[96:99]
	v_mfma_f32_16x16x32_bf16 v[92:95], v[136:139], v[198:201], v[92:95]
	v_mfma_f32_16x16x32_bf16 v[92:95], v[132:135], v[194:197], v[92:95]
	s_setprio 0
	s_setprio 1
	v_mfma_f32_16x16x32_bf16 v[100:103], v[148:151], v[164:167], v[100:103]
	v_mfma_f32_16x16x32_bf16 v[100:103], v[152:155], v[168:171], v[100:103]
	v_mfma_f32_16x16x32_bf16 v[104:107], v[160:163], v[168:171], v[104:107]
	v_mfma_f32_16x16x32_bf16 v[104:107], v[156:159], v[164:167], v[104:107]
	v_mfma_f32_16x16x32_bf16 v[112:115], v[156:159], v[172:175], v[112:115]
	v_mfma_f32_16x16x32_bf16 v[112:115], v[160:163], v[176:179], v[112:115]
	v_mfma_f32_16x16x32_bf16 v[108:111], v[152:155], v[176:179], v[108:111]
	v_mfma_f32_16x16x32_bf16 v[108:111], v[148:151], v[172:175], v[108:111]
	v_mfma_f32_16x16x32_bf16 v[116:119], v[148:151], v[180:183], v[116:119]
	v_mfma_f32_16x16x32_bf16 v[116:119], v[152:155], v[184:187], v[116:119]
	v_mfma_f32_16x16x32_bf16 v[120:123], v[160:163], v[184:187], v[120:123]
	v_mfma_f32_16x16x32_bf16 v[120:123], v[156:159], v[180:183], v[120:123]
	v_mfma_f32_16x16x32_bf16 v[128:131], v[156:159], v[194:197], v[128:131]
	v_mfma_f32_16x16x32_bf16 v[128:131], v[160:163], v[198:201], v[128:131]
	s_setprio 2
	s_barrier
	v_mfma_f32_16x16x32_bf16 v[124:127], v[152:155], v[198:201], v[124:127]
	v_mfma_f32_16x16x32_bf16 v[124:127], v[148:151], v[194:197], v[124:127]
	s_setprio 0
	s_cmpk_gt_u32 s28, 0x55
	s_cbranch_scc1 .LBB0_651
	s_mov_b32 s28, s29
	s_branch .LBB0_645
